# hyena conv epilogue packed into 4xbf16 LDS accesses (L=4096), PEER sort into 16 table regions
# speedup vs baseline: 1.0923x; 1.0072x over previous
; __device__ __forceinline__ float key2f(unsigned k) { return __uint_as_float((k & 0x80000000u) ? (k & 0x7fffffffu) : ~k); }
; __device__ void ph_peer(const float* __restrict__ SC, const bf16_t* __restrict__ H  , const float* __restrict__ gffn, const unsigned char* __restrict__ U, const unsigned char* __restrict__ V, float* X, const float* __restrict__ fgain) {
;     ...
;             for (int u = 0; u < 2; ++u) {
;                 const float bs = key2f(best[u] & ~255u);
;                 const int pos = 255 - (int)(best[u] & 255u);
;                 const int e0 = __shfl(n0[u], (pos >> 4) & 15), e1 = __shfl(n1[u], pos & 15);
;                 const float mxs = __shfl(bs, 0);
;                 float e = lane < 16 ? __expf((bs - mxs) * rstd) : 0.f;
;                 const float den = row16_sum(e);
;                 const int iv = __shfl(e0 * 128 + e1, lane & 15); const float gv = __shfl(e / den, lane & 15);
;                 const int hh = h + u;
;                 if (grp == (hh & 3)) { if (hh < 4) { idx_lo = iv; g_lo = gv; } else { idx_hi = iv; g_hi = gv; } } }
.Lpeer_partB:
	v_lshrrev_b32_e32 v2, 11, v72
	v_lshrrev_b32_e32 v3, 6, v131
	v_lshl_add_u32 v2, v2, 3, v91
	v_mul_u32_u24_e32 v3, 0x1c00, v3
	v_mul_u32_u24_e32 v2, 0x70, v2
	v_and_b32_e32 v4, 15, v74
	v_add_u32_e32 v3, 0x12000, v3
	v_add_u32_e32 v2, v3, v2
	v_add_u32_e32 v5, v2, v4
	v_lshl_add_u32 v6, v4, 2, v2
	ds_read_u8 v7, v5 offset:96
	ds_read_u8 v8, v5 offset:544
	ds_read_b32 v9, v6 offset:32
	ds_read_b32 v10, v6 offset:480
	ds_read_b32 v11, v2 offset:32
	ds_read_b32 v13, v2 offset:480
	s_waitcnt lgkmcnt(4)
	v_not_b32_e32 v7, v7
	v_not_b32_e32 v8, v8
	v_bfe_u32 v14, v7, 4, 4
	v_and_b32_e32 v7, 15, v7
	v_bfe_u32 v15, v8, 4, 4
	v_and_b32_e32 v8, 15, v8
	v_add_u32_e32 v14, v2, v14
	v_add_u32_e32 v7, v2, v7
	v_add_u32_e32 v15, v2, v15
	v_add_u32_e32 v8, v2, v8
	ds_read_u8 v14, v14
	ds_read_u8 v7, v7 offset:16
	ds_read_u8 v15, v15 offset:448
	ds_read_u8 v8, v8 offset:464
	s_waitcnt lgkmcnt(4)
	v_sub_f32_e32 v9, v9, v11
	v_sub_f32_e32 v10, v10, v13
	v_mul_f32_e32 v9, v12, v9
	v_mul_f32_e32 v10, v12, v10
	v_mul_f32_e32 v9, 0x3fb8aa3b, v9
	v_mul_f32_e32 v10, 0x3fb8aa3b, v10
	v_exp_f32_e32 v9, v9
	v_exp_f32_e32 v10, v10
	s_nop 1
	v_add_f32_dpp v11, v9, v9 quad_perm:[1,0,3,2] row_mask:0xf bank_mask:0xf bound_ctrl:1
	v_add_f32_dpp v13, v10, v10 quad_perm:[1,0,3,2] row_mask:0xf bank_mask:0xf bound_ctrl:1
	s_nop 0
	v_add_f32_dpp v11, v11, v11 quad_perm:[2,3,0,1] row_mask:0xf bank_mask:0xf bound_ctrl:1
	v_add_f32_dpp v13, v13, v13 quad_perm:[2,3,0,1] row_mask:0xf bank_mask:0xf bound_ctrl:1
	s_nop 0
	v_add_f32_dpp v11, v11, v11 row_half_mirror row_mask:0xf bank_mask:0xf bound_ctrl:1
	v_add_f32_dpp v13, v13, v13 row_half_mirror row_mask:0xf bank_mask:0xf bound_ctrl:1
	s_nop 0
	v_add_f32_dpp v11, v11, v11 row_mirror row_mask:0xf bank_mask:0xf bound_ctrl:1
	v_add_f32_dpp v13, v13, v13 row_mirror row_mask:0xf bank_mask:0xf bound_ctrl:1
	s_nop 0
	v_div_scale_f32 v16, s[0:1], v11, v11, v9
	v_div_scale_f32 v17, s[0:1], v13, v13, v10
	v_rcp_f32_e32 v18, v16
	v_rcp_f32_e32 v19, v17
	s_nop 0
	v_fma_f32 v20, -v16, v18, 1.0
	v_fma_f32 v21, -v17, v19, 1.0
	v_fmac_f32_e32 v18, v20, v18
	v_fmac_f32_e32 v19, v21, v19
	v_div_scale_f32 v20, vcc, v9, v11, v9
	v_mul_f32_e32 v22, v20, v18
	v_fma_f32 v24, -v16, v22, v20
	v_fmac_f32_e32 v22, v24, v18
	v_fma_f32 v20, -v16, v22, v20
	v_div_fmas_f32 v20, v20, v18, v22
	v_div_fixup_f32 v73, v20, v11, v9
	v_div_scale_f32 v21, vcc, v10, v13, v10
	v_mul_f32_e32 v23, v21, v19
	v_fma_f32 v25, -v17, v23, v21
	v_fmac_f32_e32 v23, v25, v19
	v_fma_f32 v21, -v17, v23, v21
	v_div_fmas_f32 v21, v21, v19, v23
	v_div_fixup_f32 v158, v21, v13, v10
	s_waitcnt lgkmcnt(0)
	v_and_b32_e32 v14, 0x7f, v14
	v_and_b32_e32 v7, 0x7f, v7
	v_and_b32_e32 v15, 0x7f, v15
	v_and_b32_e32 v8, 0x7f, v8
	v_lshl_or_b32 v14, v14, 7, v7
	v_lshl_or_b32 v15, v15, 7, v8
	v_xor_b32_e32 v156, 0x3fff, v14
	v_xor_b32_e32 v157, 0x3fff, v15
	v_lshrrev_b32_e32 v2, 10, v156
	v_lshrrev_b32_e32 v3, 10, v157
	s_mov_b32 s2, 0
	v_mov_b32_e32 v6, 0
	v_mov_b32_e32 v7, 0
	v_cmp_eq_u32_e64 s[0:1], 0, v2
	v_cmp_eq_u32_e64 s[6:7], 0, v3
	s_nop 1
	v_mbcnt_lo_u32_b32 v4, s0, 0
	v_mbcnt_lo_u32_b32 v5, s6, 0
	v_mbcnt_hi_u32_b32 v4, s1, v4
	v_mbcnt_hi_u32_b32 v5, s7, v5
	s_bcnt1_i32_b64 s14, s[0:1]
	s_bcnt1_i32_b64 s15, s[6:7]
	v_add_u32_e32 v4, s2, v4
	s_add_i32 s14, s2, s14
	s_nop 0
	v_add_u32_e32 v5, s14, v5
	s_add_i32 s2, s14, s15
	v_cndmask_b32_e64 v6, v6, v4, s[0:1]
	v_cndmask_b32_e64 v7, v7, v5, s[6:7]
	v_cmp_eq_u32_e64 s[0:1], 1, v2
	v_cmp_eq_u32_e64 s[6:7], 1, v3
	s_nop 1
	v_mbcnt_lo_u32_b32 v4, s0, 0
	v_mbcnt_lo_u32_b32 v5, s6, 0
	v_mbcnt_hi_u32_b32 v4, s1, v4
	v_mbcnt_hi_u32_b32 v5, s7, v5
	s_bcnt1_i32_b64 s14, s[0:1]
	s_bcnt1_i32_b64 s15, s[6:7]
	v_add_u32_e32 v4, s2, v4
	s_add_i32 s14, s2, s14
	s_nop 0
	v_add_u32_e32 v5, s14, v5
	s_add_i32 s2, s14, s15
	v_cndmask_b32_e64 v6, v6, v4, s[0:1]
	v_cndmask_b32_e64 v7, v7, v5, s[6:7]
	v_cmp_eq_u32_e64 s[0:1], 2, v2
	v_cmp_eq_u32_e64 s[6:7], 2, v3
	s_nop 1
	v_mbcnt_lo_u32_b32 v4, s0, 0
	v_mbcnt_lo_u32_b32 v5, s6, 0
	v_mbcnt_hi_u32_b32 v4, s1, v4
	v_mbcnt_hi_u32_b32 v5, s7, v5
	s_bcnt1_i32_b64 s14, s[0:1]
	s_bcnt1_i32_b64 s15, s[6:7]
	v_add_u32_e32 v4, s2, v4
	s_add_i32 s14, s2, s14
	s_nop 0
	v_add_u32_e32 v5, s14, v5
	s_add_i32 s2, s14, s15
	v_cndmask_b32_e64 v6, v6, v4, s[0:1]
	v_cndmask_b32_e64 v7, v7, v5, s[6:7]
	v_cmp_eq_u32_e64 s[0:1], 3, v2
	v_cmp_eq_u32_e64 s[6:7], 3, v3
	s_nop 1
	v_mbcnt_lo_u32_b32 v4, s0, 0
	v_mbcnt_lo_u32_b32 v5, s6, 0
	v_mbcnt_hi_u32_b32 v4, s1, v4
	v_mbcnt_hi_u32_b32 v5, s7, v5
	s_bcnt1_i32_b64 s14, s[0:1]
	s_bcnt1_i32_b64 s15, s[6:7]
	v_add_u32_e32 v4, s2, v4
	s_add_i32 s14, s2, s14
	s_nop 0
	v_add_u32_e32 v5, s14, v5
	s_add_i32 s2, s14, s15
	v_cndmask_b32_e64 v6, v6, v4, s[0:1]
	v_cndmask_b32_e64 v7, v7, v5, s[6:7]
	v_cmp_eq_u32_e64 s[0:1], 4, v2
	v_cmp_eq_u32_e64 s[6:7], 4, v3
	s_nop 1
	v_mbcnt_lo_u32_b32 v4, s0, 0
	v_mbcnt_lo_u32_b32 v5, s6, 0
	v_mbcnt_hi_u32_b32 v4, s1, v4
	v_mbcnt_hi_u32_b32 v5, s7, v5
	s_bcnt1_i32_b64 s14, s[0:1]
	s_bcnt1_i32_b64 s15, s[6:7]
	v_add_u32_e32 v4, s2, v4
	s_add_i32 s14, s2, s14
	s_nop 0
	v_add_u32_e32 v5, s14, v5
	s_add_i32 s2, s14, s15
	v_cndmask_b32_e64 v6, v6, v4, s[0:1]
; __device__ void ph_peer(const float* __restrict__ SC, const bf16_t* __restrict__ H  , const float* __restrict__ gffn, const unsigned char* __restrict__ U, const unsigned char* __restrict__ V, float* X, const float* __restrict__ fgain) {
;     ...
;                 const int iv = __shfl(e0 * 128 + e1, lane & 15); const float gv = __shfl(e / den, lane & 15);
;                 const int hh = h + u;
;                 if (grp == (hh & 3)) { if (hh < 4) { idx_lo = iv; g_lo = gv; } else { idx_hi = iv; g_hi = gv; } } }
	v_cndmask_b32_e64 v7, v7, v5, s[6:7]
	v_cmp_eq_u32_e64 s[0:1], 5, v2
	v_cmp_eq_u32_e64 s[6:7], 5, v3
	s_nop 1
	v_mbcnt_lo_u32_b32 v4, s0, 0
	v_mbcnt_lo_u32_b32 v5, s6, 0
	v_mbcnt_hi_u32_b32 v4, s1, v4
	v_mbcnt_hi_u32_b32 v5, s7, v5
	s_bcnt1_i32_b64 s14, s[0:1]
	s_bcnt1_i32_b64 s15, s[6:7]
	v_add_u32_e32 v4, s2, v4
	s_add_i32 s14, s2, s14
	s_nop 0
	v_add_u32_e32 v5, s14, v5
	s_add_i32 s2, s14, s15
	v_cndmask_b32_e64 v6, v6, v4, s[0:1]
	v_cndmask_b32_e64 v7, v7, v5, s[6:7]
	v_cmp_eq_u32_e64 s[0:1], 6, v2
	v_cmp_eq_u32_e64 s[6:7], 6, v3
	s_nop 1
	v_mbcnt_lo_u32_b32 v4, s0, 0
	v_mbcnt_lo_u32_b32 v5, s6, 0
	v_mbcnt_hi_u32_b32 v4, s1, v4
	v_mbcnt_hi_u32_b32 v5, s7, v5
	s_bcnt1_i32_b64 s14, s[0:1]
	s_bcnt1_i32_b64 s15, s[6:7]
	v_add_u32_e32 v4, s2, v4
	s_add_i32 s14, s2, s14
	s_nop 0
	v_add_u32_e32 v5, s14, v5
	s_add_i32 s2, s14, s15
	v_cndmask_b32_e64 v6, v6, v4, s[0:1]
	v_cndmask_b32_e64 v7, v7, v5, s[6:7]
	v_cmp_eq_u32_e64 s[0:1], 7, v2
	v_cmp_eq_u32_e64 s[6:7], 7, v3
	s_nop 1
	v_mbcnt_lo_u32_b32 v4, s0, 0
	v_mbcnt_lo_u32_b32 v5, s6, 0
	v_mbcnt_hi_u32_b32 v4, s1, v4
	v_mbcnt_hi_u32_b32 v5, s7, v5
	s_bcnt1_i32_b64 s14, s[0:1]
	s_bcnt1_i32_b64 s15, s[6:7]
	v_add_u32_e32 v4, s2, v4
	s_add_i32 s14, s2, s14
	s_nop 0
	v_add_u32_e32 v5, s14, v5
	s_add_i32 s2, s14, s15
	v_cndmask_b32_e64 v6, v6, v4, s[0:1]
	v_cndmask_b32_e64 v7, v7, v5, s[6:7]
	v_cmp_eq_u32_e64 s[0:1], 8, v2
	v_cmp_eq_u32_e64 s[6:7], 8, v3
	s_nop 1
	v_mbcnt_lo_u32_b32 v4, s0, 0
	v_mbcnt_lo_u32_b32 v5, s6, 0
	v_mbcnt_hi_u32_b32 v4, s1, v4
	v_mbcnt_hi_u32_b32 v5, s7, v5
	s_bcnt1_i32_b64 s14, s[0:1]
	s_bcnt1_i32_b64 s15, s[6:7]
	v_add_u32_e32 v4, s2, v4
	s_add_i32 s14, s2, s14
	s_nop 0
	v_add_u32_e32 v5, s14, v5
	s_add_i32 s2, s14, s15
	v_cndmask_b32_e64 v6, v6, v4, s[0:1]
	v_cndmask_b32_e64 v7, v7, v5, s[6:7]
	v_cmp_eq_u32_e64 s[0:1], 9, v2
	v_cmp_eq_u32_e64 s[6:7], 9, v3
	s_nop 1
	v_mbcnt_lo_u32_b32 v4, s0, 0
	v_mbcnt_lo_u32_b32 v5, s6, 0
	v_mbcnt_hi_u32_b32 v4, s1, v4
	v_mbcnt_hi_u32_b32 v5, s7, v5
	s_bcnt1_i32_b64 s14, s[0:1]
	s_bcnt1_i32_b64 s15, s[6:7]
	v_add_u32_e32 v4, s2, v4
	s_add_i32 s14, s2, s14
	s_nop 0
	v_add_u32_e32 v5, s14, v5
	s_add_i32 s2, s14, s15
	v_cndmask_b32_e64 v6, v6, v4, s[0:1]
	v_cndmask_b32_e64 v7, v7, v5, s[6:7]
	v_cmp_eq_u32_e64 s[0:1], 10, v2
	v_cmp_eq_u32_e64 s[6:7], 10, v3
	s_nop 1
	v_mbcnt_lo_u32_b32 v4, s0, 0
	v_mbcnt_lo_u32_b32 v5, s6, 0
	v_mbcnt_hi_u32_b32 v4, s1, v4
	v_mbcnt_hi_u32_b32 v5, s7, v5
	s_bcnt1_i32_b64 s14, s[0:1]
	s_bcnt1_i32_b64 s15, s[6:7]
	v_add_u32_e32 v4, s2, v4
	s_add_i32 s14, s2, s14
	s_nop 0
	v_add_u32_e32 v5, s14, v5
	s_add_i32 s2, s14, s15
	v_cndmask_b32_e64 v6, v6, v4, s[0:1]
	v_cndmask_b32_e64 v7, v7, v5, s[6:7]
	v_cmp_eq_u32_e64 s[0:1], 11, v2
	v_cmp_eq_u32_e64 s[6:7], 11, v3
	s_nop 1
	v_mbcnt_lo_u32_b32 v4, s0, 0
	v_mbcnt_lo_u32_b32 v5, s6, 0
	v_mbcnt_hi_u32_b32 v4, s1, v4
	v_mbcnt_hi_u32_b32 v5, s7, v5
	s_bcnt1_i32_b64 s14, s[0:1]
	s_bcnt1_i32_b64 s15, s[6:7]
	v_add_u32_e32 v4, s2, v4
	s_add_i32 s14, s2, s14
	s_nop 0
	v_add_u32_e32 v5, s14, v5
	s_add_i32 s2, s14, s15
	v_cndmask_b32_e64 v6, v6, v4, s[0:1]
	v_cndmask_b32_e64 v7, v7, v5, s[6:7]
	v_cmp_eq_u32_e64 s[0:1], 12, v2
	v_cmp_eq_u32_e64 s[6:7], 12, v3
	s_nop 1
	v_mbcnt_lo_u32_b32 v4, s0, 0
	v_mbcnt_lo_u32_b32 v5, s6, 0
	v_mbcnt_hi_u32_b32 v4, s1, v4
	v_mbcnt_hi_u32_b32 v5, s7, v5
	s_bcnt1_i32_b64 s14, s[0:1]
	s_bcnt1_i32_b64 s15, s[6:7]
	v_add_u32_e32 v4, s2, v4
	s_add_i32 s14, s2, s14
	s_nop 0
	v_add_u32_e32 v5, s14, v5
	s_add_i32 s2, s14, s15
	v_cndmask_b32_e64 v6, v6, v4, s[0:1]
	v_cndmask_b32_e64 v7, v7, v5, s[6:7]
	v_cmp_eq_u32_e64 s[0:1], 13, v2
	v_cmp_eq_u32_e64 s[6:7], 13, v3
	s_nop 1
	v_mbcnt_lo_u32_b32 v4, s0, 0
	v_mbcnt_lo_u32_b32 v5, s6, 0
	v_mbcnt_hi_u32_b32 v4, s1, v4
	v_mbcnt_hi_u32_b32 v5, s7, v5
	s_bcnt1_i32_b64 s14, s[0:1]
	s_bcnt1_i32_b64 s15, s[6:7]
	v_add_u32_e32 v4, s2, v4
	s_add_i32 s14, s2, s14
	s_nop 0
	v_add_u32_e32 v5, s14, v5
	s_add_i32 s2, s14, s15
	v_cndmask_b32_e64 v6, v6, v4, s[0:1]
	v_cndmask_b32_e64 v7, v7, v5, s[6:7]
	v_cmp_eq_u32_e64 s[0:1], 14, v2
	v_cmp_eq_u32_e64 s[6:7], 14, v3
	s_nop 1
	v_mbcnt_lo_u32_b32 v4, s0, 0
	v_mbcnt_lo_u32_b32 v5, s6, 0
	v_mbcnt_hi_u32_b32 v4, s1, v4
	v_mbcnt_hi_u32_b32 v5, s7, v5
	s_bcnt1_i32_b64 s14, s[0:1]
	s_bcnt1_i32_b64 s15, s[6:7]
	v_add_u32_e32 v4, s2, v4
	s_add_i32 s14, s2, s14
	s_nop 0
	v_add_u32_e32 v5, s14, v5
	s_add_i32 s2, s14, s15
	v_cndmask_b32_e64 v6, v6, v4, s[0:1]
	v_cndmask_b32_e64 v7, v7, v5, s[6:7]
	v_cmp_eq_u32_e64 s[0:1], 15, v2
	v_cmp_eq_u32_e64 s[6:7], 15, v3
	s_nop 1
	v_mbcnt_lo_u32_b32 v4, s0, 0
	v_mbcnt_lo_u32_b32 v5, s6, 0
	v_mbcnt_hi_u32_b32 v4, s1, v4
	v_mbcnt_hi_u32_b32 v5, s7, v5
	s_bcnt1_i32_b64 s14, s[0:1]
	s_bcnt1_i32_b64 s15, s[6:7]
	v_add_u32_e32 v4, s2, v4
	s_add_i32 s14, s2, s14
	s_nop 0
	v_add_u32_e32 v5, s14, v5
	s_add_i32 s2, s14, s15
	v_cndmask_b32_e64 v6, v6, v4, s[0:1]
	v_cndmask_b32_e64 v7, v7, v5, s[6:7]
	v_lshrrev_b32_e32 v8, 6, v131
	v_mul_u32_u24_e32 v8, 0x2400, v8
	v_lshl_add_u32 v9, v6, 2, v8
	v_lshl_add_u32 v10, v7, 2, v8
	ds_write_b32 v9, v156
	ds_write_b32 v10, v157
	ds_write_b32 v9, v73 offset:512
	ds_write_b32 v10, v158 offset:512

; __device__ __forceinline__ float key2f(unsigned k) { return __uint_as_float((k & 0x80000000u) ? (k & 0x7fffffffu) : ~k); }
; __device__ void ph_peer(const float* __restrict__ SC, const bf16_t* __restrict__ H  , const float* __restrict__ gffn, const unsigned char* __restrict__ U, const unsigned char* __restrict__ V, float* X, const float* __restrict__ fgain) {
;     ...
;             for (int u = 0; u < 2; ++u) {
;                 const float bs = key2f(best[u] & ~255u);
;                 const int pos = 255 - (int)(best[u] & 255u);
;                 const int e0 = __shfl(n0[u], (pos >> 4) & 15), e1 = __shfl(n1[u], pos & 15);
;                 const float mxs = __shfl(bs, 0);
;                 float e = lane < 16 ? __expf((bs - mxs) * rstd) : 0.f;
;                 const float den = row16_sum(e);
;                 const int iv = __shfl(e0 * 128 + e1, lane & 15); const float gv = __shfl(e / den, lane & 15);
;                 const int hh = h + u;
;                 if (grp == (hh & 3)) { if (hh < 4) { idx_lo = iv; g_lo = gv; } else { idx_hi = iv; g_hi = gv; } } }
.Lpeer_partB_b:
	v_lshrrev_b32_e32 v2, 11, v72
	v_lshrrev_b32_e32 v3, 6, v131
	v_lshl_add_u32 v2, v2, 3, v91
	v_mul_u32_u24_e32 v3, 0x1c00, v3
	v_mul_u32_u24_e32 v2, 0x70, v2
	v_and_b32_e32 v4, 15, v74
	v_add_u32_e32 v3, 0x12000, v3
	v_add_u32_e32 v2, v3, v2
	v_add_u32_e32 v5, v2, v4
	v_lshl_add_u32 v6, v4, 2, v2
	ds_read_u8 v7, v5 offset:96
	ds_read_u8 v8, v5 offset:544
	ds_read_b32 v9, v6 offset:32
	ds_read_b32 v10, v6 offset:480
	ds_read_b32 v11, v2 offset:32
	ds_read_b32 v13, v2 offset:480
	s_waitcnt lgkmcnt(4)
	v_not_b32_e32 v7, v7
	v_not_b32_e32 v8, v8
	v_bfe_u32 v14, v7, 4, 4
	v_and_b32_e32 v7, 15, v7
	v_bfe_u32 v15, v8, 4, 4
	v_and_b32_e32 v8, 15, v8
	v_add_u32_e32 v14, v2, v14
	v_add_u32_e32 v7, v2, v7
	v_add_u32_e32 v15, v2, v15
	v_add_u32_e32 v8, v2, v8
	ds_read_u8 v14, v14
	ds_read_u8 v7, v7 offset:16
	ds_read_u8 v15, v15 offset:448
	ds_read_u8 v8, v8 offset:464
	s_waitcnt lgkmcnt(4)
	v_sub_f32_e32 v9, v9, v11
	v_sub_f32_e32 v10, v10, v13
	v_mul_f32_e32 v9, v12, v9
	v_mul_f32_e32 v10, v12, v10
	v_mul_f32_e32 v9, 0x3fb8aa3b, v9
	v_mul_f32_e32 v10, 0x3fb8aa3b, v10
	v_exp_f32_e32 v9, v9
	v_exp_f32_e32 v10, v10
	s_nop 1
	v_add_f32_dpp v11, v9, v9 quad_perm:[1,0,3,2] row_mask:0xf bank_mask:0xf bound_ctrl:1
	v_add_f32_dpp v13, v10, v10 quad_perm:[1,0,3,2] row_mask:0xf bank_mask:0xf bound_ctrl:1
	s_nop 0
	v_add_f32_dpp v11, v11, v11 quad_perm:[2,3,0,1] row_mask:0xf bank_mask:0xf bound_ctrl:1
	v_add_f32_dpp v13, v13, v13 quad_perm:[2,3,0,1] row_mask:0xf bank_mask:0xf bound_ctrl:1
	s_nop 0
	v_add_f32_dpp v11, v11, v11 row_half_mirror row_mask:0xf bank_mask:0xf bound_ctrl:1
	v_add_f32_dpp v13, v13, v13 row_half_mirror row_mask:0xf bank_mask:0xf bound_ctrl:1
	s_nop 0
	v_add_f32_dpp v11, v11, v11 row_mirror row_mask:0xf bank_mask:0xf bound_ctrl:1
	v_add_f32_dpp v13, v13, v13 row_mirror row_mask:0xf bank_mask:0xf bound_ctrl:1
	s_nop 0
	v_div_scale_f32 v16, s[0:1], v11, v11, v9
	v_div_scale_f32 v17, s[0:1], v13, v13, v10
	v_rcp_f32_e32 v18, v16
	v_rcp_f32_e32 v19, v17
	s_nop 0
	v_fma_f32 v20, -v16, v18, 1.0
	v_fma_f32 v21, -v17, v19, 1.0
	v_fmac_f32_e32 v18, v20, v18
	v_fmac_f32_e32 v19, v21, v19
	v_div_scale_f32 v20, vcc, v9, v11, v9
	v_mul_f32_e32 v22, v20, v18
	v_fma_f32 v24, -v16, v22, v20
	v_fmac_f32_e32 v22, v24, v18
	v_fma_f32 v20, -v16, v22, v20
	v_div_fmas_f32 v20, v20, v18, v22
	v_div_fixup_f32 v73, v20, v11, v9
	v_div_scale_f32 v21, vcc, v10, v13, v10
	v_mul_f32_e32 v23, v21, v19
	v_fma_f32 v25, -v17, v23, v21
	v_fmac_f32_e32 v23, v25, v19
	v_fma_f32 v21, -v17, v23, v21
	v_div_fmas_f32 v21, v21, v19, v23
	v_div_fixup_f32 v158, v21, v13, v10
	s_waitcnt lgkmcnt(0)
	v_and_b32_e32 v14, 0x7f, v14
	v_and_b32_e32 v7, 0x7f, v7
	v_and_b32_e32 v15, 0x7f, v15
	v_and_b32_e32 v8, 0x7f, v8
	v_lshl_or_b32 v14, v14, 7, v7
	v_lshl_or_b32 v15, v15, 7, v8
	v_xor_b32_e32 v156, 0x3fff, v14
	v_xor_b32_e32 v157, 0x3fff, v15
	v_lshrrev_b32_e32 v2, 10, v156
	v_lshrrev_b32_e32 v3, 10, v157
	s_mov_b32 s2, 0
	v_mov_b32_e32 v6, 0
	v_mov_b32_e32 v7, 0
	v_cmp_eq_u32_e64 s[0:1], 0, v2
	v_cmp_eq_u32_e64 s[6:7], 0, v3
	s_nop 1
	v_mbcnt_lo_u32_b32 v4, s0, 0
	v_mbcnt_lo_u32_b32 v5, s6, 0
	v_mbcnt_hi_u32_b32 v4, s1, v4
	v_mbcnt_hi_u32_b32 v5, s7, v5
	s_bcnt1_i32_b64 s14, s[0:1]
	s_bcnt1_i32_b64 s15, s[6:7]
	v_add_u32_e32 v4, s2, v4
	s_add_i32 s14, s2, s14
	s_nop 0
	v_add_u32_e32 v5, s14, v5
	s_add_i32 s2, s14, s15
	v_cndmask_b32_e64 v6, v6, v4, s[0:1]
	v_cndmask_b32_e64 v7, v7, v5, s[6:7]
	v_cmp_eq_u32_e64 s[0:1], 1, v2
	v_cmp_eq_u32_e64 s[6:7], 1, v3
	s_nop 1
	v_mbcnt_lo_u32_b32 v4, s0, 0
	v_mbcnt_lo_u32_b32 v5, s6, 0
	v_mbcnt_hi_u32_b32 v4, s1, v4
	v_mbcnt_hi_u32_b32 v5, s7, v5
	s_bcnt1_i32_b64 s14, s[0:1]
	s_bcnt1_i32_b64 s15, s[6:7]
	v_add_u32_e32 v4, s2, v4
	s_add_i32 s14, s2, s14
	s_nop 0
	v_add_u32_e32 v5, s14, v5
	s_add_i32 s2, s14, s15
	v_cndmask_b32_e64 v6, v6, v4, s[0:1]
	v_cndmask_b32_e64 v7, v7, v5, s[6:7]
	v_cmp_eq_u32_e64 s[0:1], 2, v2
	v_cmp_eq_u32_e64 s[6:7], 2, v3
	s_nop 1
	v_mbcnt_lo_u32_b32 v4, s0, 0
	v_mbcnt_lo_u32_b32 v5, s6, 0
	v_mbcnt_hi_u32_b32 v4, s1, v4
	v_mbcnt_hi_u32_b32 v5, s7, v5
	s_bcnt1_i32_b64 s14, s[0:1]
	s_bcnt1_i32_b64 s15, s[6:7]
	v_add_u32_e32 v4, s2, v4
	s_add_i32 s14, s2, s14
	s_nop 0
	v_add_u32_e32 v5, s14, v5
	s_add_i32 s2, s14, s15
	v_cndmask_b32_e64 v6, v6, v4, s[0:1]
	v_cndmask_b32_e64 v7, v7, v5, s[6:7]
	v_cmp_eq_u32_e64 s[0:1], 3, v2
	v_cmp_eq_u32_e64 s[6:7], 3, v3
	s_nop 1
	v_mbcnt_lo_u32_b32 v4, s0, 0
	v_mbcnt_lo_u32_b32 v5, s6, 0
	v_mbcnt_hi_u32_b32 v4, s1, v4
	v_mbcnt_hi_u32_b32 v5, s7, v5
	s_bcnt1_i32_b64 s14, s[0:1]
	s_bcnt1_i32_b64 s15, s[6:7]
	v_add_u32_e32 v4, s2, v4
	s_add_i32 s14, s2, s14
	s_nop 0
	v_add_u32_e32 v5, s14, v5
	s_add_i32 s2, s14, s15
	v_cndmask_b32_e64 v6, v6, v4, s[0:1]
	v_cndmask_b32_e64 v7, v7, v5, s[6:7]
	v_cmp_eq_u32_e64 s[0:1], 4, v2
	v_cmp_eq_u32_e64 s[6:7], 4, v3
	s_nop 1
	v_mbcnt_lo_u32_b32 v4, s0, 0
	v_mbcnt_lo_u32_b32 v5, s6, 0
	v_mbcnt_hi_u32_b32 v4, s1, v4
	v_mbcnt_hi_u32_b32 v5, s7, v5
	s_bcnt1_i32_b64 s14, s[0:1]
	s_bcnt1_i32_b64 s15, s[6:7]
	v_add_u32_e32 v4, s2, v4
	s_add_i32 s14, s2, s14
	s_nop 0
	v_add_u32_e32 v5, s14, v5
	s_add_i32 s2, s14, s15
	v_cndmask_b32_e64 v6, v6, v4, s[0:1]
	v_cndmask_b32_e64 v7, v7, v5, s[6:7]
	v_cmp_eq_u32_e64 s[0:1], 5, v2
	v_cmp_eq_u32_e64 s[6:7], 5, v3
	s_nop 1
	v_mbcnt_lo_u32_b32 v4, s0, 0
	v_mbcnt_lo_u32_b32 v5, s6, 0
	v_mbcnt_hi_u32_b32 v4, s1, v4
	v_mbcnt_hi_u32_b32 v5, s7, v5
	s_bcnt1_i32_b64 s14, s[0:1]
	s_bcnt1_i32_b64 s15, s[6:7]
	v_add_u32_e32 v4, s2, v4
	s_add_i32 s14, s2, s14
	s_nop 0
	v_add_u32_e32 v5, s14, v5
	s_add_i32 s2, s14, s15
	v_cndmask_b32_e64 v6, v6, v4, s[0:1]
	v_cndmask_b32_e64 v7, v7, v5, s[6:7]
	v_cmp_eq_u32_e64 s[0:1], 6, v2
; __device__ void ph_peer(const float* __restrict__ SC, const bf16_t* __restrict__ H  , const float* __restrict__ gffn, const unsigned char* __restrict__ U, const unsigned char* __restrict__ V, float* X, const float* __restrict__ fgain) {
;     ...
;                 const int iv = __shfl(e0 * 128 + e1, lane & 15); const float gv = __shfl(e / den, lane & 15);
;                 const int hh = h + u;
;                 if (grp == (hh & 3)) { if (hh < 4) { idx_lo = iv; g_lo = gv; } else { idx_hi = iv; g_hi = gv; } } }
	v_cmp_eq_u32_e64 s[6:7], 6, v3
	s_nop 1
	v_mbcnt_lo_u32_b32 v4, s0, 0
	v_mbcnt_lo_u32_b32 v5, s6, 0
	v_mbcnt_hi_u32_b32 v4, s1, v4
	v_mbcnt_hi_u32_b32 v5, s7, v5
	s_bcnt1_i32_b64 s14, s[0:1]
	s_bcnt1_i32_b64 s15, s[6:7]
	v_add_u32_e32 v4, s2, v4
	s_add_i32 s14, s2, s14
	s_nop 0
	v_add_u32_e32 v5, s14, v5
	s_add_i32 s2, s14, s15
	v_cndmask_b32_e64 v6, v6, v4, s[0:1]
	v_cndmask_b32_e64 v7, v7, v5, s[6:7]
	v_cmp_eq_u32_e64 s[0:1], 7, v2
	v_cmp_eq_u32_e64 s[6:7], 7, v3
	s_nop 1
	v_mbcnt_lo_u32_b32 v4, s0, 0
	v_mbcnt_lo_u32_b32 v5, s6, 0
	v_mbcnt_hi_u32_b32 v4, s1, v4
	v_mbcnt_hi_u32_b32 v5, s7, v5
	s_bcnt1_i32_b64 s14, s[0:1]
	s_bcnt1_i32_b64 s15, s[6:7]
	v_add_u32_e32 v4, s2, v4
	s_add_i32 s14, s2, s14
	s_nop 0
	v_add_u32_e32 v5, s14, v5
	s_add_i32 s2, s14, s15
	v_cndmask_b32_e64 v6, v6, v4, s[0:1]
	v_cndmask_b32_e64 v7, v7, v5, s[6:7]
	v_cmp_eq_u32_e64 s[0:1], 8, v2
	v_cmp_eq_u32_e64 s[6:7], 8, v3
	s_nop 1
	v_mbcnt_lo_u32_b32 v4, s0, 0
	v_mbcnt_lo_u32_b32 v5, s6, 0
	v_mbcnt_hi_u32_b32 v4, s1, v4
	v_mbcnt_hi_u32_b32 v5, s7, v5
	s_bcnt1_i32_b64 s14, s[0:1]
	s_bcnt1_i32_b64 s15, s[6:7]
	v_add_u32_e32 v4, s2, v4
	s_add_i32 s14, s2, s14
	s_nop 0
	v_add_u32_e32 v5, s14, v5
	s_add_i32 s2, s14, s15
	v_cndmask_b32_e64 v6, v6, v4, s[0:1]
	v_cndmask_b32_e64 v7, v7, v5, s[6:7]
	v_cmp_eq_u32_e64 s[0:1], 9, v2
	v_cmp_eq_u32_e64 s[6:7], 9, v3
	s_nop 1
	v_mbcnt_lo_u32_b32 v4, s0, 0
	v_mbcnt_lo_u32_b32 v5, s6, 0
	v_mbcnt_hi_u32_b32 v4, s1, v4
	v_mbcnt_hi_u32_b32 v5, s7, v5
	s_bcnt1_i32_b64 s14, s[0:1]
	s_bcnt1_i32_b64 s15, s[6:7]
	v_add_u32_e32 v4, s2, v4
	s_add_i32 s14, s2, s14
	s_nop 0
	v_add_u32_e32 v5, s14, v5
	s_add_i32 s2, s14, s15
	v_cndmask_b32_e64 v6, v6, v4, s[0:1]
	v_cndmask_b32_e64 v7, v7, v5, s[6:7]
	v_cmp_eq_u32_e64 s[0:1], 10, v2
	v_cmp_eq_u32_e64 s[6:7], 10, v3
	s_nop 1
	v_mbcnt_lo_u32_b32 v4, s0, 0
	v_mbcnt_lo_u32_b32 v5, s6, 0
	v_mbcnt_hi_u32_b32 v4, s1, v4
	v_mbcnt_hi_u32_b32 v5, s7, v5
	s_bcnt1_i32_b64 s14, s[0:1]
	s_bcnt1_i32_b64 s15, s[6:7]
	v_add_u32_e32 v4, s2, v4
	s_add_i32 s14, s2, s14
	s_nop 0
	v_add_u32_e32 v5, s14, v5
	s_add_i32 s2, s14, s15
	v_cndmask_b32_e64 v6, v6, v4, s[0:1]
	v_cndmask_b32_e64 v7, v7, v5, s[6:7]
	v_cmp_eq_u32_e64 s[0:1], 11, v2
	v_cmp_eq_u32_e64 s[6:7], 11, v3
	s_nop 1
	v_mbcnt_lo_u32_b32 v4, s0, 0
	v_mbcnt_lo_u32_b32 v5, s6, 0
	v_mbcnt_hi_u32_b32 v4, s1, v4
	v_mbcnt_hi_u32_b32 v5, s7, v5
	s_bcnt1_i32_b64 s14, s[0:1]
	s_bcnt1_i32_b64 s15, s[6:7]
	v_add_u32_e32 v4, s2, v4
	s_add_i32 s14, s2, s14
	s_nop 0
	v_add_u32_e32 v5, s14, v5
	s_add_i32 s2, s14, s15
	v_cndmask_b32_e64 v6, v6, v4, s[0:1]
	v_cndmask_b32_e64 v7, v7, v5, s[6:7]
	v_cmp_eq_u32_e64 s[0:1], 12, v2
	v_cmp_eq_u32_e64 s[6:7], 12, v3
	s_nop 1
	v_mbcnt_lo_u32_b32 v4, s0, 0
	v_mbcnt_lo_u32_b32 v5, s6, 0
	v_mbcnt_hi_u32_b32 v4, s1, v4
	v_mbcnt_hi_u32_b32 v5, s7, v5
	s_bcnt1_i32_b64 s14, s[0:1]
	s_bcnt1_i32_b64 s15, s[6:7]
	v_add_u32_e32 v4, s2, v4
	s_add_i32 s14, s2, s14
	s_nop 0
	v_add_u32_e32 v5, s14, v5
	s_add_i32 s2, s14, s15
	v_cndmask_b32_e64 v6, v6, v4, s[0:1]
	v_cndmask_b32_e64 v7, v7, v5, s[6:7]
	v_cmp_eq_u32_e64 s[0:1], 13, v2
	v_cmp_eq_u32_e64 s[6:7], 13, v3
	s_nop 1
	v_mbcnt_lo_u32_b32 v4, s0, 0
	v_mbcnt_lo_u32_b32 v5, s6, 0
	v_mbcnt_hi_u32_b32 v4, s1, v4
	v_mbcnt_hi_u32_b32 v5, s7, v5
	s_bcnt1_i32_b64 s14, s[0:1]
	s_bcnt1_i32_b64 s15, s[6:7]
	v_add_u32_e32 v4, s2, v4
	s_add_i32 s14, s2, s14
	s_nop 0
	v_add_u32_e32 v5, s14, v5
	s_add_i32 s2, s14, s15
	v_cndmask_b32_e64 v6, v6, v4, s[0:1]
	v_cndmask_b32_e64 v7, v7, v5, s[6:7]
	v_cmp_eq_u32_e64 s[0:1], 14, v2
	v_cmp_eq_u32_e64 s[6:7], 14, v3
	s_nop 1
	v_mbcnt_lo_u32_b32 v4, s0, 0
	v_mbcnt_lo_u32_b32 v5, s6, 0
	v_mbcnt_hi_u32_b32 v4, s1, v4
	v_mbcnt_hi_u32_b32 v5, s7, v5
	s_bcnt1_i32_b64 s14, s[0:1]
	s_bcnt1_i32_b64 s15, s[6:7]
	v_add_u32_e32 v4, s2, v4
	s_add_i32 s14, s2, s14
	s_nop 0
	v_add_u32_e32 v5, s14, v5
	s_add_i32 s2, s14, s15
	v_cndmask_b32_e64 v6, v6, v4, s[0:1]
	v_cndmask_b32_e64 v7, v7, v5, s[6:7]
	v_cmp_eq_u32_e64 s[0:1], 15, v2
	v_cmp_eq_u32_e64 s[6:7], 15, v3
	s_nop 1
	v_mbcnt_lo_u32_b32 v4, s0, 0
	v_mbcnt_lo_u32_b32 v5, s6, 0
	v_mbcnt_hi_u32_b32 v4, s1, v4
	v_mbcnt_hi_u32_b32 v5, s7, v5
	s_bcnt1_i32_b64 s14, s[0:1]
	s_bcnt1_i32_b64 s15, s[6:7]
	v_add_u32_e32 v4, s2, v4
	s_add_i32 s14, s2, s14
	s_nop 0
	v_add_u32_e32 v5, s14, v5
	s_add_i32 s2, s14, s15
	v_cndmask_b32_e64 v6, v6, v4, s[0:1]
	v_cndmask_b32_e64 v7, v7, v5, s[6:7]
	v_lshrrev_b32_e32 v8, 6, v131
	v_mul_u32_u24_e32 v8, 0x2400, v8
	v_lshl_add_u32 v9, v6, 2, v8
	v_lshl_add_u32 v10, v7, 2, v8
	ds_write_b32 v9, v156 offset:1536
	ds_write_b32 v10, v157 offset:1536
	ds_write_b32 v9, v73 offset:2048
	ds_write_b32 v10, v158 offset:2048
	s_waitcnt vmcnt(0) lgkmcnt(0)
; __device__ __forceinline__ unsigned cvt_pk_bf16(float lo, float hi) { unsigned r; asm volatile("v_cvt_pk_bf16_f32 %0, %1, %2" : "=v"(r) : "v"(lo), "v"(hi)); return r; }
; __device__ __forceinline__ float bflo(unsigned w) { return __uint_as_float(w << 16); }
; __device__ __forceinline__ float bfhi(unsigned w) { return __uint_as_float(w & 0xffff0000u); }
; __device__ void ph_peer(const float* __restrict__ SC, const bf16_t* __restrict__ H  , const float* __restrict__ gffn, const unsigned char* __restrict__ U, const unsigned char* __restrict__ V, float* X, const float* __restrict__ fgain) {
;     ...
;         {   const u32x4* hp = (const u32x4*)(H + (size_t)tok * 1024 + 64 * sub);
; #pragma unroll
;             for (int q = 0; q < 8; ++q) { const u32x4 w = hp[q];
;                 const float4 ga = *(const float4*)(gffn + 64 * sub + q * 8), gb = *(const float4*)(gffn + 64 * sub + q * 8 + 4);
;                 hf2[q * 4 + 0] = cvt_pk_bf16(bflo(w.x) * rstd * ga.x, bfhi(w.x) * rstd * ga.y);
;                 hf2[q * 4 + 1] = cvt_pk_bf16(bflo(w.y) * rstd * ga.z, bfhi(w.y) * rstd * ga.w);
;                 hf2[q * 4 + 2] = cvt_pk_bf16(bflo(w.z) * rstd * gb.x, bfhi(w.z) * rstd * gb.y);
;                 hf2[q * 4 + 3] = cvt_pk_bf16(bflo(w.w) * rstd * gb.z, bfhi(w.w) * rstd * gb.w); } }
	v_lshlrev_b32_e32 v2, 16, v218
	v_and_b32_e32 v3, 0xffff0000, v218
	v_mul_f32_e32 v2, v12, v2
	v_mul_f32_e32 v3, v12, v3
	v_mul_f32_e32 v2, v64, v2
	v_mul_f32_e32 v3, v65, v3
	v_cvt_pk_bf16_f32 v212, v2, v3
	v_lshlrev_b32_e32 v2, 16, v219
	v_and_b32_e32 v3, 0xffff0000, v219
	v_mul_f32_e32 v2, v12, v2
	v_mul_f32_e32 v3, v12, v3
	v_mul_f32_e32 v2, v66, v2
	v_mul_f32_e32 v3, v67, v3
	v_cvt_pk_bf16_f32 v213, v2, v3
	v_lshlrev_b32_e32 v2, 16, v220
	v_and_b32_e32 v3, 0xffff0000, v220
	v_mul_f32_e32 v2, v12, v2
	v_mul_f32_e32 v3, v12, v3
	v_mul_f32_e32 v2, v68, v2
	v_mul_f32_e32 v3, v69, v3
	v_cvt_pk_bf16_f32 v214, v2, v3
	v_lshlrev_b32_e32 v2, 16, v221
	v_and_b32_e32 v3, 0xffff0000, v221
	v_mul_f32_e32 v2, v12, v2
	v_mul_f32_e32 v3, v12, v3
	v_mul_f32_e32 v2, v70, v2
	v_mul_f32_e32 v3, v71, v3
	v_cvt_pk_bf16_f32 v215, v2, v3
	v_lshlrev_b32_e32 v2, 16, v222
	v_and_b32_e32 v3, 0xffff0000, v222
	v_mul_f32_e32 v2, v12, v2
	v_mul_f32_e32 v3, v12, v3
	v_mul_f32_e32 v2, v32, v2
	v_mul_f32_e32 v3, v33, v3
	v_cvt_pk_bf16_f32 v218, v2, v3
	v_lshlrev_b32_e32 v2, 16, v223
	v_and_b32_e32 v3, 0xffff0000, v223
	v_mul_f32_e32 v2, v12, v2
	v_mul_f32_e32 v3, v12, v3
	v_mul_f32_e32 v2, v34, v2
	v_mul_f32_e32 v3, v35, v3
	v_cvt_pk_bf16_f32 v219, v2, v3
	v_lshlrev_b32_e32 v2, 16, v224
	v_and_b32_e32 v3, 0xffff0000, v224
	v_mul_f32_e32 v2, v12, v2
	v_mul_f32_e32 v3, v12, v3
	v_mul_f32_e32 v2, v36, v2
	v_mul_f32_e32 v3, v37, v3
	v_cvt_pk_bf16_f32 v220, v2, v3
	v_lshlrev_b32_e32 v2, 16, v225
	v_and_b32_e32 v3, 0xffff0000, v225
	v_mul_f32_e32 v2, v12, v2
	v_mul_f32_e32 v3, v12, v3
	v_mul_f32_e32 v2, v38, v2
	v_mul_f32_e32 v3, v39, v3
	v_cvt_pk_bf16_f32 v221, v2, v3
	v_lshlrev_b32_e32 v2, 16, v226
	v_and_b32_e32 v3, 0xffff0000, v226
	v_mul_f32_e32 v2, v12, v2
	v_mul_f32_e32 v3, v12, v3
	v_mul_f32_e32 v2, v40, v2
	v_mul_f32_e32 v3, v41, v3
	v_cvt_pk_bf16_f32 v222, v2, v3
	v_lshlrev_b32_e32 v2, 16, v227
	v_and_b32_e32 v3, 0xffff0000, v227
	v_mul_f32_e32 v2, v12, v2
	v_mul_f32_e32 v3, v12, v3
	v_mul_f32_e32 v2, v42, v2
	v_mul_f32_e32 v3, v43, v3
	v_cvt_pk_bf16_f32 v223, v2, v3
	v_lshlrev_b32_e32 v2, 16, v228
	v_and_b32_e32 v3, 0xffff0000, v228
	v_mul_f32_e32 v2, v12, v2
	v_mul_f32_e32 v3, v12, v3
	v_mul_f32_e32 v2, v44, v2
	v_mul_f32_e32 v3, v45, v3
	v_cvt_pk_bf16_f32 v224, v2, v3
	v_lshlrev_b32_e32 v2, 16, v229
	v_and_b32_e32 v3, 0xffff0000, v229
	v_mul_f32_e32 v2, v12, v2
	v_mul_f32_e32 v3, v12, v3
	v_mul_f32_e32 v2, v46, v2
	v_mul_f32_e32 v3, v47, v3
	v_cvt_pk_bf16_f32 v225, v2, v3
	v_lshlrev_b32_e32 v2, 16, v230
	v_and_b32_e32 v3, 0xffff0000, v230
	v_mul_f32_e32 v2, v12, v2
	v_mul_f32_e32 v3, v12, v3
	v_mul_f32_e32 v2, v48, v2
	v_mul_f32_e32 v3, v49, v3
	v_cvt_pk_bf16_f32 v226, v2, v3
	v_lshlrev_b32_e32 v2, 16, v231
	v_and_b32_e32 v3, 0xffff0000, v231
	v_mul_f32_e32 v2, v12, v2
	v_mul_f32_e32 v3, v12, v3
	v_mul_f32_e32 v2, v50, v2
	v_mul_f32_e32 v3, v51, v3
	v_cvt_pk_bf16_f32 v227, v2, v3
	v_lshlrev_b32_e32 v2, 16, v232
	v_and_b32_e32 v3, 0xffff0000, v232
	v_mul_f32_e32 v2, v12, v2
	v_mul_f32_e32 v3, v12, v3
	v_mul_f32_e32 v2, v52, v2
	v_mul_f32_e32 v3, v53, v3
	v_cvt_pk_bf16_f32 v228, v2, v3
	v_lshlrev_b32_e32 v2, 16, v233
	v_and_b32_e32 v3, 0xffff0000, v233
	v_mul_f32_e32 v2, v12, v2
	v_mul_f32_e32 v3, v12, v3
	v_mul_f32_e32 v2, v54, v2
	v_mul_f32_e32 v3, v55, v3
	v_cvt_pk_bf16_f32 v229, v2, v3
	v_lshlrev_b32_e32 v2, 16, v234
	v_and_b32_e32 v3, 0xffff0000, v234
	v_mul_f32_e32 v2, v12, v2
	v_mul_f32_e32 v3, v12, v3
	v_mul_f32_e32 v2, v56, v2
	v_mul_f32_e32 v3, v57, v3
	v_cvt_pk_bf16_f32 v230, v2, v3
	v_lshlrev_b32_e32 v2, 16, v235
	v_and_b32_e32 v3, 0xffff0000, v235
	v_mul_f32_e32 v2, v12, v2
	v_mul_f32_e32 v3, v12, v3
	v_mul_f32_e32 v2, v58, v2
	v_mul_f32_e32 v3, v59, v3
	v_cvt_pk_bf16_f32 v231, v2, v3
	v_lshlrev_b32_e32 v2, 16, v236
	v_and_b32_e32 v3, 0xffff0000, v236
	v_mul_f32_e32 v2, v12, v2
	v_mul_f32_e32 v3, v12, v3
	v_mul_f32_e32 v2, v60, v2
	v_mul_f32_e32 v3, v61, v3
	v_cvt_pk_bf16_f32 v232, v2, v3
	v_lshlrev_b32_e32 v2, 16, v237
	v_and_b32_e32 v3, 0xffff0000, v237
	v_mul_f32_e32 v2, v12, v2
	v_mul_f32_e32 v3, v12, v3
; __device__ __forceinline__ unsigned cvt_pk_bf16(float lo, float hi) { unsigned r; asm volatile("v_cvt_pk_bf16_f32 %0, %1, %2" : "=v"(r) : "v"(lo), "v"(hi)); return r; }
; __device__ __forceinline__ float bflo(unsigned w) { return __uint_as_float(w << 16); }
; __device__ __forceinline__ float bfhi(unsigned w) { return __uint_as_float(w & 0xffff0000u); }
; __device__ void ph_peer(const float* __restrict__ SC, const bf16_t* __restrict__ H  , const float* __restrict__ gffn, const unsigned char* __restrict__ U, const unsigned char* __restrict__ V, float* X, const float* __restrict__ fgain) {
;     ...
;                 hf2[q * 4 + 3] = cvt_pk_bf16(bflo(w.w) * rstd * gb.z, bfhi(w.w) * rstd * gb.w); } }
;         const int half = lane >> 5, c32 = lane & 31;
;         float acc[32];
; #pragma unroll
;         for (int i = 0; i < 32; ++i) acc[i] = 0.f;
;         __builtin_amdgcn_s_setprio(1);
; #pragma unroll 1
;         for (int it = 0; it < 32; ++it) {
;             const int src = (it * 4 + grp) & 63;
;             const int e = __shfl(it < 16 ? idx_lo : idx_hi, src);
;             const float gt = __shfl(it < 16 ? g_lo : g_hi, src);
;             const u32x4* up = (const u32x4*)(U + (size_t)e * 768 + 48 * sub);
;             const u32x4 u0 = up[0], u1 = up[1], u2 = up[2];
	v_mul_f32_e32 v2, v62, v2
	v_mul_f32_e32 v3, v63, v3
	v_cvt_pk_bf16_f32 v233, v2, v3
	v_lshlrev_b32_e32 v2, 16, v238
	v_and_b32_e32 v3, 0xffff0000, v238
	v_mul_f32_e32 v2, v12, v2
	v_mul_f32_e32 v3, v12, v3
	v_mul_f32_e32 v2, v98, v2
	v_mul_f32_e32 v3, v99, v3
	v_cvt_pk_bf16_f32 v234, v2, v3
	v_lshlrev_b32_e32 v2, 16, v239
	v_and_b32_e32 v3, 0xffff0000, v239
	v_mul_f32_e32 v2, v12, v2
	v_mul_f32_e32 v3, v12, v3
	v_mul_f32_e32 v2, v100, v2
	v_mul_f32_e32 v3, v101, v3
	v_cvt_pk_bf16_f32 v235, v2, v3
	v_lshlrev_b32_e32 v2, 16, v240
	v_and_b32_e32 v3, 0xffff0000, v240
	v_mul_f32_e32 v2, v12, v2
	v_mul_f32_e32 v3, v12, v3
	v_mul_f32_e32 v2, v102, v2
	v_mul_f32_e32 v3, v103, v3
	v_cvt_pk_bf16_f32 v236, v2, v3
	v_lshlrev_b32_e32 v2, 16, v241
	v_and_b32_e32 v3, 0xffff0000, v241
	v_mul_f32_e32 v2, v12, v2
	v_mul_f32_e32 v3, v12, v3
	v_mul_f32_e32 v2, v104, v2
	v_mul_f32_e32 v3, v105, v3
	v_cvt_pk_bf16_f32 v237, v2, v3
	v_lshlrev_b32_e32 v2, 16, v242
	v_and_b32_e32 v3, 0xffff0000, v242
	v_mul_f32_e32 v2, v12, v2
	v_mul_f32_e32 v3, v12, v3
	v_mul_f32_e32 v2, v106, v2
	v_mul_f32_e32 v3, v107, v3
	v_cvt_pk_bf16_f32 v238, v2, v3
	v_lshlrev_b32_e32 v2, 16, v243
	v_and_b32_e32 v3, 0xffff0000, v243
	v_mul_f32_e32 v2, v12, v2
	v_mul_f32_e32 v3, v12, v3
	v_mul_f32_e32 v2, v108, v2
	v_mul_f32_e32 v3, v109, v3
	v_cvt_pk_bf16_f32 v239, v2, v3
	v_lshlrev_b32_e32 v2, 16, v244
	v_and_b32_e32 v3, 0xffff0000, v244
	v_mul_f32_e32 v2, v12, v2
	v_mul_f32_e32 v3, v12, v3
	v_mul_f32_e32 v2, v110, v2
	v_mul_f32_e32 v3, v111, v3
	v_cvt_pk_bf16_f32 v240, v2, v3
	v_lshlrev_b32_e32 v2, 16, v245
	v_and_b32_e32 v3, 0xffff0000, v245
	v_mul_f32_e32 v2, v12, v2
	v_mul_f32_e32 v3, v12, v3
	v_mul_f32_e32 v2, v112, v2
	v_mul_f32_e32 v3, v113, v3
	v_cvt_pk_bf16_f32 v241, v2, v3
	v_lshlrev_b32_e32 v2, 16, v246
	v_and_b32_e32 v3, 0xffff0000, v246
	v_mul_f32_e32 v2, v12, v2
	v_mul_f32_e32 v3, v12, v3
	v_mul_f32_e32 v2, v114, v2
	v_mul_f32_e32 v3, v115, v3
	v_cvt_pk_bf16_f32 v242, v2, v3
	v_lshlrev_b32_e32 v2, 16, v247
	v_and_b32_e32 v3, 0xffff0000, v247
	v_mul_f32_e32 v2, v12, v2
	v_mul_f32_e32 v3, v12, v3
	v_mul_f32_e32 v2, v116, v2
	v_mul_f32_e32 v3, v117, v3
	v_cvt_pk_bf16_f32 v243, v2, v3
	v_lshlrev_b32_e32 v2, 16, v248
	v_and_b32_e32 v3, 0xffff0000, v248
	v_mul_f32_e32 v2, v12, v2
	v_mul_f32_e32 v3, v12, v3
	v_mul_f32_e32 v2, v118, v2
	v_mul_f32_e32 v3, v119, v3
	v_cvt_pk_bf16_f32 v244, v2, v3
	v_lshlrev_b32_e32 v2, 16, v249
	v_and_b32_e32 v3, 0xffff0000, v249
	v_mul_f32_e32 v2, v12, v2
	v_mul_f32_e32 v3, v12, v3
	v_mul_f32_e32 v2, v120, v2
	v_mul_f32_e32 v3, v121, v3
	v_cvt_pk_bf16_f32 v245, v2, v3
	s_setprio 1
	v_mov_b32_e32 v126, 0
	s_mov_b32 s0, 0
	s_mov_b32 s1, 0
	v_mov_b32_e32 v127, v126
	v_mov_b32_e32 v144, v126
	v_mov_b32_e32 v145, v126
	v_mov_b32_e32 v122, v126
	v_mov_b32_e32 v123, v126
	v_mov_b32_e32 v124, v126
	v_mov_b32_e32 v125, v126
	v_mov_b32_e32 v114, v126
	v_mov_b32_e32 v115, v126
	v_mov_b32_e32 v118, v126
	v_mov_b32_e32 v119, v126
	v_mov_b32_e32 v116, v126
	v_mov_b32_e32 v117, v126
	v_mov_b32_e32 v120, v126
	v_mov_b32_e32 v121, v126
	v_mov_b32_e32 v106, v126
	v_mov_b32_e32 v107, v126
	v_mov_b32_e32 v110, v126
	v_mov_b32_e32 v111, v126
	v_mov_b32_e32 v108, v126
	v_mov_b32_e32 v109, v126
	v_mov_b32_e32 v112, v126
	v_mov_b32_e32 v113, v126
	v_mov_b32_e32 v98, v126
	v_mov_b32_e32 v99, v126
	v_mov_b32_e32 v102, v126
	v_mov_b32_e32 v103, v126
	v_mov_b32_e32 v100, v126
	v_mov_b32_e32 v101, v126
	v_mov_b32_e32 v104, v126
	v_mov_b32_e32 v105, v126
	s_movk_i32 s14, 0x300
	s_mov_b32 s16, 0x3e6d3388
	s_mov_b32 s24, 0x3f07dc22
	s_mov_b32 s28, 0x3f35f0e3
	s_mov_b32 s30, 0xbe11a98e
	s_mov_b32 s36, 0x3e027906
	s_barrier
	v_lshrrev_b32_e32 v61, 6, v131
	v_mul_u32_u24_e32 v61, 0x2400, v61
	v_lshl_add_u32 v61, v91, 2, v61
	s_mov_b32 s1, 0
	ds_read_b32 v56, v61
	ds_read_b32 v57, v61 offset:512
	v_add_u32_e32 v61, 16, v61
	s_add_i32 s1, s1, 1
	s_waitcnt lgkmcnt(1)
	v_mad_i64_i32 v[0:1], s[6:7], v56, s14, v[80:81]
	global_load_dwordx4 v[32:35], v[0:1], off
	global_load_dwordx4 v[36:39], v[0:1], off offset:16
	global_load_dwordx4 v[40:43], v[0:1], off offset:32

; __device__ __forceinline__ float bf2f(unsigned short b) { return __uint_as_float(((unsigned)b) << 16); }
; __device__ __forceinline__ bf16_t f2bf(float f) { return (bf16_t)(cvt_pk_bf16(f, 0.f) & 0xffffu); }
; template <int L>
; __device__ __forceinline__ void hy_conv(const bf16_t* F, const bf16_t* Bbuf, const bf16_t* Vbuf, bf16_t* Obuf, float skipv) {
;     ...
; #pragma unroll
;     for (int rho = 0; rho < 4; ++rho)
; #pragma unroll
;         for (int r = 0; r < 4; ++r) { const int t = T0a + 64 * m + rho + 4 * (4 * kg + r); const int off = b * LP + 192 + t;
;             Obuf[off] = f2bf(acc0[rho][r] + bf2f(Vbuf[off]) * skipv);
;             Obuf[off + TS] = f2bf(acc1[rho][r] + bf2f(Vbuf[off + TS]) * skipv); }
.LBB0_400:
	s_or_b64 exec, exec, s[28:29]
	s_nop 0
	v_add3_u32 v56, v202, v200, v201
	v_add_lshl_u32 v58, v56, v203, 1
	v_add_u32_e32 v57, 0x180, v58
	v_readlane_b32 s7, v253, 58
	v_readlane_b32 s6, v253, 57
	v_readlane_b32 s14, v251, 24
	v_add_u32_e32 v56, s7, v57
	v_add_u32_e32 v57, s6, v57
	v_readlane_b32 s15, v251, 25
	ds_read_b64 v[58:59], v56 offset:0
	s_waitcnt vmcnt(0)
	ds_read_b64 v[248:249], v56 offset:8
	s_waitcnt lgkmcnt(1)
	v_lshlrev_b32_e32 v255, 16, v58
	v_fmac_f32_e32 v68, v199, v255
	v_and_b32_e32 v255, 0xffff0000, v58
	v_fmac_f32_e32 v60, v199, v255
	v_lshlrev_b32_e32 v255, 16, v59
	v_fmac_f32_e32 v52, v199, v255
	v_and_b32_e32 v255, 0xffff0000, v59
	v_fmac_f32_e32 v48, v199, v255
	v_cvt_pk_bf16_f32 v58, v68, v60
	v_cvt_pk_bf16_f32 v59, v52, v48
	ds_write_b64 v57, v[58:59] offset:0
	ds_read_b64 v[58:59], v56 offset:16
	s_waitcnt lgkmcnt(2)
	v_lshlrev_b32_e32 v255, 16, v248
	v_fmac_f32_e32 v69, v199, v255
	v_and_b32_e32 v255, 0xffff0000, v248
	v_fmac_f32_e32 v61, v199, v255
	v_lshlrev_b32_e32 v255, 16, v249
	v_fmac_f32_e32 v53, v199, v255
	v_and_b32_e32 v255, 0xffff0000, v249
	v_fmac_f32_e32 v49, v199, v255
	v_cvt_pk_bf16_f32 v248, v69, v61
	v_cvt_pk_bf16_f32 v249, v53, v49
	ds_write_b64 v57, v[248:249] offset:8
	ds_read_b64 v[248:249], v56 offset:24
	s_waitcnt lgkmcnt(2)
	v_lshlrev_b32_e32 v255, 16, v58
	v_fmac_f32_e32 v70, v199, v255
	v_and_b32_e32 v255, 0xffff0000, v58
	v_fmac_f32_e32 v62, v199, v255
	v_lshlrev_b32_e32 v255, 16, v59
	v_fmac_f32_e32 v54, v199, v255
	v_and_b32_e32 v255, 0xffff0000, v59
	v_fmac_f32_e32 v50, v199, v255
	v_cvt_pk_bf16_f32 v58, v70, v62
	v_cvt_pk_bf16_f32 v59, v54, v50
	ds_write_b64 v57, v[58:59] offset:16
	ds_read_b64 v[58:59], v56 offset:512
	s_waitcnt lgkmcnt(2)
	v_lshlrev_b32_e32 v255, 16, v248
	v_fmac_f32_e32 v71, v199, v255
	v_and_b32_e32 v255, 0xffff0000, v248
	v_fmac_f32_e32 v63, v199, v255
	v_lshlrev_b32_e32 v255, 16, v249
	v_fmac_f32_e32 v55, v199, v255
	v_and_b32_e32 v255, 0xffff0000, v249
	v_fmac_f32_e32 v51, v199, v255
	v_cvt_pk_bf16_f32 v248, v71, v63
	v_cvt_pk_bf16_f32 v249, v55, v51
	ds_write_b64 v57, v[248:249] offset:24
	ds_read_b64 v[248:249], v56 offset:520
	s_waitcnt lgkmcnt(2)
	v_lshlrev_b32_e32 v255, 16, v58
	v_fmac_f32_e32 v44, v199, v255
	v_and_b32_e32 v255, 0xffff0000, v58
	v_fmac_f32_e32 v40, v199, v255
	v_lshlrev_b32_e32 v255, 16, v59
	v_fmac_f32_e32 v36, v199, v255
	v_and_b32_e32 v255, 0xffff0000, v59
	v_fmac_f32_e32 v32, v199, v255
	v_cvt_pk_bf16_f32 v58, v44, v40
	v_cvt_pk_bf16_f32 v59, v36, v32
	ds_write_b64 v57, v[58:59] offset:512
	ds_read_b64 v[58:59], v56 offset:528
	s_waitcnt lgkmcnt(2)
	v_lshlrev_b32_e32 v255, 16, v248
	v_fmac_f32_e32 v45, v199, v255
	v_and_b32_e32 v255, 0xffff0000, v248
	v_fmac_f32_e32 v41, v199, v255
	v_lshlrev_b32_e32 v255, 16, v249
	v_fmac_f32_e32 v37, v199, v255
	v_and_b32_e32 v255, 0xffff0000, v249
	v_fmac_f32_e32 v33, v199, v255
	v_cvt_pk_bf16_f32 v248, v45, v41
	v_cvt_pk_bf16_f32 v249, v37, v33
	ds_write_b64 v57, v[248:249] offset:520
	ds_read_b64 v[248:249], v56 offset:536
	s_waitcnt lgkmcnt(2)
	v_lshlrev_b32_e32 v255, 16, v58
	v_fmac_f32_e32 v46, v199, v255
	v_and_b32_e32 v255, 0xffff0000, v58
	v_fmac_f32_e32 v42, v199, v255
	v_lshlrev_b32_e32 v255, 16, v59
	v_fmac_f32_e32 v38, v199, v255
	v_and_b32_e32 v255, 0xffff0000, v59
	v_fmac_f32_e32 v34, v199, v255
	v_cvt_pk_bf16_f32 v58, v46, v42
	v_cvt_pk_bf16_f32 v59, v38, v34
	ds_write_b64 v57, v[58:59] offset:528
	s_waitcnt lgkmcnt(1)
	v_lshlrev_b32_e32 v255, 16, v248
	v_fmac_f32_e32 v47, v199, v255
	v_and_b32_e32 v255, 0xffff0000, v248
	v_fmac_f32_e32 v43, v199, v255
	v_lshlrev_b32_e32 v255, 16, v249
	v_fmac_f32_e32 v39, v199, v255
	v_and_b32_e32 v255, 0xffff0000, v249
	v_fmac_f32_e32 v35, v199, v255
	v_cvt_pk_bf16_f32 v248, v47, v43
	v_cvt_pk_bf16_f32 v249, v39, v35
	ds_write_b64 v57, v[248:249] offset:536
	s_lshl_b64 s[6:7], s[26:27], 15
	s_add_u32 s26, s14, s6
	s_addc_u32 s27, s15, s7
	v_lshlrev_b32_e32 v36, 16, v28
	v_and_b32_e32 v28, 0xffff0000, v28
	s_and_b64 vcc, exec, s[76:77]
	s_waitcnt lgkmcnt(0)
	s_barrier
; #define HY_MUL8(sv, xv, o) do { o.x = cvt_pk_bf16(bflo(sv.x) * bflo(xv.x), bfhi(sv.x) * bfhi(xv.x)); o.y = cvt_pk_bf16(bflo(sv.y) * bflo(xv.y), bfhi(sv.y) * bfhi(xv.y)); \
;         o.z = cvt_pk_bf16(bflo(sv.z) * bflo(xv.z), bfhi(sv.z) * bfhi(xv.z)); o.w = cvt_pk_bf16(bflo(sv.w) * bflo(xv.w), bfhi(sv.w) * bfhi(xv.w)); } while (0)
; template <int L>
; __device__ void ph_hyena(const bf16_t* __restrict__ ZT, bf16_t* __restrict__ YT, const bf16_t* __restrict__ G0  , const float* __restrict__ skip  , unsigned char* smem) {
;     ...
; #pragma unroll
;         for (int k = 0; k < 4; ++k) { const u32x4 sv = *(const u32x4*)(Z + loff[k]); u32x4 o; HY_MUL8(sv, xv[k], o); *(u32x4*)(YT + (size_t)c * GT + (size_t)(tid + NTHR * k) * 8) = o; }
	ds_read_b128 v[32:35], v187
	s_waitcnt lgkmcnt(0)
	v_lshlrev_b32_e32 v37, 16, v32
	v_and_b32_e32 v32, 0xffff0000, v32
	v_mul_f32_e32 v36, v37, v36
	v_mul_f32_e32 v28, v32, v28
	v_cvt_pk_bf16_f32 v28, v36, v28
	v_lshlrev_b32_e32 v32, 16, v29
	v_lshlrev_b32_e32 v36, 16, v33
	v_and_b32_e32 v33, 0xffff0000, v33
	v_and_b32_e32 v29, 0xffff0000, v29
	v_mul_f32_e32 v32, v36, v32
	v_mul_f32_e32 v29, v33, v29
	v_cvt_pk_bf16_f32 v29, v32, v29
	v_lshlrev_b32_e32 v32, 16, v30
	v_lshlrev_b32_e32 v33, 16, v34
	v_mul_f32_e32 v32, v33, v32
	v_and_b32_e32 v33, 0xffff0000, v34
	v_and_b32_e32 v30, 0xffff0000, v30
	v_mul_f32_e32 v30, v33, v30
	v_cvt_pk_bf16_f32 v30, v32, v30
	v_lshlrev_b32_e32 v32, 16, v31
	v_lshlrev_b32_e32 v33, 16, v35
	v_mul_f32_e32 v32, v33, v32
	v_and_b32_e32 v33, 0xffff0000, v35
	v_and_b32_e32 v31, 0xffff0000, v31
	v_mul_f32_e32 v31, v33, v31
	v_cvt_pk_bf16_f32 v31, v32, v31
	v_lshl_add_u64 v[32:33], s[26:27], 0, v[120:121]
	global_store_dwordx4 v[32:33], v[28:31], off
	ds_read_b128 v[28:31], v188
	v_lshlrev_b32_e32 v32, 16, v24
	v_and_b32_e32 v24, 0xffff0000, v24
	s_waitcnt lgkmcnt(0)
	v_lshlrev_b32_e32 v33, 16, v28
	v_and_b32_e32 v28, 0xffff0000, v28
	v_mul_f32_e32 v32, v33, v32
	v_mul_f32_e32 v24, v28, v24
	v_cvt_pk_bf16_f32 v24, v32, v24
	v_lshlrev_b32_e32 v28, 16, v25
	v_lshlrev_b32_e32 v32, 16, v29
	v_and_b32_e32 v29, 0xffff0000, v29
	v_and_b32_e32 v25, 0xffff0000, v25
	v_mul_f32_e32 v28, v32, v28
	v_mul_f32_e32 v25, v29, v25
	v_cvt_pk_bf16_f32 v25, v28, v25
	v_lshlrev_b32_e32 v28, 16, v26
	v_lshlrev_b32_e32 v29, 16, v30
	v_mul_f32_e32 v28, v29, v28
	v_and_b32_e32 v29, 0xffff0000, v30
	v_and_b32_e32 v26, 0xffff0000, v26
	v_mul_f32_e32 v26, v29, v26
	v_cvt_pk_bf16_f32 v26, v28, v26
	v_lshlrev_b32_e32 v28, 16, v27
	v_lshlrev_b32_e32 v29, 16, v31
	v_mul_f32_e32 v28, v29, v28
	v_and_b32_e32 v29, 0xffff0000, v31
	v_and_b32_e32 v27, 0xffff0000, v27
	v_mul_f32_e32 v27, v29, v27
	v_cvt_pk_bf16_f32 v27, v28, v27
	v_lshl_add_u64 v[28:29], s[26:27], 0, v[122:123]
	global_store_dwordx4 v[28:29], v[24:27], off
	ds_read_b128 v[24:27], v189
	v_lshlrev_b32_e32 v28, 16, v20
	v_and_b32_e32 v20, 0xffff0000, v20
	s_waitcnt lgkmcnt(0)
	v_lshlrev_b32_e32 v29, 16, v24
	v_and_b32_e32 v24, 0xffff0000, v24
	v_mul_f32_e32 v28, v29, v28
	v_mul_f32_e32 v20, v24, v20
	v_cvt_pk_bf16_f32 v20, v28, v20
	v_lshlrev_b32_e32 v24, 16, v21
	v_lshlrev_b32_e32 v28, 16, v25
	v_and_b32_e32 v25, 0xffff0000, v25
	v_and_b32_e32 v21, 0xffff0000, v21
	v_mul_f32_e32 v24, v28, v24
	v_mul_f32_e32 v21, v25, v21
	v_cvt_pk_bf16_f32 v21, v24, v21
	v_lshlrev_b32_e32 v24, 16, v22
	v_lshlrev_b32_e32 v25, 16, v26
	v_mul_f32_e32 v24, v25, v24
	v_and_b32_e32 v25, 0xffff0000, v26
	v_and_b32_e32 v22, 0xffff0000, v22
	v_mul_f32_e32 v22, v25, v22
	v_cvt_pk_bf16_f32 v22, v24, v22
	v_lshlrev_b32_e32 v24, 16, v23
	v_lshlrev_b32_e32 v25, 16, v27
	v_mul_f32_e32 v24, v25, v24
	v_and_b32_e32 v25, 0xffff0000, v27
	v_and_b32_e32 v23, 0xffff0000, v23
	v_mul_f32_e32 v23, v25, v23
	v_cvt_pk_bf16_f32 v23, v24, v23
	v_lshl_add_u64 v[24:25], s[26:27], 0, v[124:125]
	global_store_dwordx4 v[24:25], v[20:23], off
	ds_read_b128 v[20:23], v191
	v_lshlrev_b32_e32 v24, 16, v16
	v_and_b32_e32 v16, 0xffff0000, v16
	s_waitcnt lgkmcnt(0)
	v_lshlrev_b32_e32 v25, 16, v20
	v_and_b32_e32 v20, 0xffff0000, v20
	v_mul_f32_e32 v24, v25, v24
	v_mul_f32_e32 v16, v20, v16
	v_cvt_pk_bf16_f32 v16, v24, v16
	v_lshlrev_b32_e32 v20, 16, v17
	v_lshlrev_b32_e32 v24, 16, v21
	v_and_b32_e32 v21, 0xffff0000, v21
	v_and_b32_e32 v17, 0xffff0000, v17
	v_mul_f32_e32 v20, v24, v20
	v_mul_f32_e32 v17, v21, v17
	v_cvt_pk_bf16_f32 v17, v20, v17
	v_lshlrev_b32_e32 v20, 16, v18
	v_lshlrev_b32_e32 v21, 16, v22
	v_mul_f32_e32 v20, v21, v20
	v_and_b32_e32 v21, 0xffff0000, v22
	v_and_b32_e32 v18, 0xffff0000, v18
	v_mul_f32_e32 v18, v21, v18
	v_cvt_pk_bf16_f32 v18, v20, v18
	v_lshlrev_b32_e32 v20, 16, v19
	v_lshlrev_b32_e32 v21, 16, v23
	v_mul_f32_e32 v20, v21, v20
	v_and_b32_e32 v21, 0xffff0000, v23
	v_and_b32_e32 v19, 0xffff0000, v19
	v_mul_f32_e32 v19, v21, v19
	v_cvt_pk_bf16_f32 v19, v20, v19
	v_lshl_add_u64 v[20:21], s[26:27], 0, v[126:127]
	s_mov_b32 s26, s74
	global_store_dwordx4 v[20:21], v[16:19], off
	s_barrier
	s_cbranch_vccnz .LBB0_567

; __device__ __forceinline__ float bf2f(unsigned short b) { return __uint_as_float(((unsigned)b) << 16); }
; __device__ __forceinline__ bf16_t f2bf(float f) { return (bf16_t)(cvt_pk_bf16(f, 0.f) & 0xffffu); }
; template <int L>
; __device__ __forceinline__ void hy_conv(const bf16_t* F, const bf16_t* Bbuf, const bf16_t* Vbuf, bf16_t* Obuf, float skipv) {
;     ...
; #pragma unroll
;     for (int rho = 0; rho < 4; ++rho)
; #pragma unroll
;         for (int r = 0; r < 4; ++r) { const int t = T0a + 64 * m + rho + 4 * (4 * kg + r); const int off = b * LP + 192 + t;
;             Obuf[off] = f2bf(acc0[rho][r] + bf2f(Vbuf[off]) * skipv);
;             Obuf[off + TS] = f2bf(acc1[rho][r] + bf2f(Vbuf[off + TS]) * skipv); }
.LBB0_473:
	s_or_b64 exec, exec, s[28:29]
	s_nop 1
	v_add3_u32 v56, v229, v227, v228
	v_add_lshl_u32 v58, v56, v230, 1
	v_add_u32_e32 v56, 0x180, v58
	v_readlane_b32 s6, v253, 57
	v_readlane_b32 s7, v253, 58
	s_nop 0
	v_add_u32_e32 v57, s6, v56
	v_add_u32_e32 v56, s7, v56
	ds_read_b64 v[58:59], v57 offset:0
	s_waitcnt vmcnt(0)
	ds_read_b64 v[248:249], v57 offset:8
	s_waitcnt lgkmcnt(1)
	v_lshlrev_b32_e32 v255, 16, v58
	v_fmac_f32_e32 v68, v226, v255
	v_and_b32_e32 v255, 0xffff0000, v58
	v_fmac_f32_e32 v60, v226, v255
	v_lshlrev_b32_e32 v255, 16, v59
	v_fmac_f32_e32 v52, v226, v255
	v_and_b32_e32 v255, 0xffff0000, v59
	v_fmac_f32_e32 v48, v226, v255
	v_cvt_pk_bf16_f32 v58, v68, v60
	v_cvt_pk_bf16_f32 v59, v52, v48
	ds_write_b64 v56, v[58:59] offset:0
	ds_read_b64 v[58:59], v57 offset:16
	s_waitcnt lgkmcnt(2)
	v_lshlrev_b32_e32 v255, 16, v248
	v_fmac_f32_e32 v69, v226, v255
	v_and_b32_e32 v255, 0xffff0000, v248
	v_fmac_f32_e32 v61, v226, v255
	v_lshlrev_b32_e32 v255, 16, v249
	v_fmac_f32_e32 v53, v226, v255
	v_and_b32_e32 v255, 0xffff0000, v249
	v_fmac_f32_e32 v49, v226, v255
	v_cvt_pk_bf16_f32 v248, v69, v61
	v_cvt_pk_bf16_f32 v249, v53, v49
	ds_write_b64 v56, v[248:249] offset:8
	ds_read_b64 v[248:249], v57 offset:24
	s_waitcnt lgkmcnt(2)
	v_lshlrev_b32_e32 v255, 16, v58
	v_fmac_f32_e32 v70, v226, v255
	v_and_b32_e32 v255, 0xffff0000, v58
	v_fmac_f32_e32 v62, v226, v255
	v_lshlrev_b32_e32 v255, 16, v59
	v_fmac_f32_e32 v54, v226, v255
	v_and_b32_e32 v255, 0xffff0000, v59
	v_fmac_f32_e32 v50, v226, v255
	v_cvt_pk_bf16_f32 v58, v70, v62
	v_cvt_pk_bf16_f32 v59, v54, v50
	ds_write_b64 v56, v[58:59] offset:16
	ds_read_b64 v[58:59], v57 offset:512
	s_waitcnt lgkmcnt(2)
	v_lshlrev_b32_e32 v255, 16, v248
	v_fmac_f32_e32 v71, v226, v255
	v_and_b32_e32 v255, 0xffff0000, v248
	v_fmac_f32_e32 v63, v226, v255
	v_lshlrev_b32_e32 v255, 16, v249
	v_fmac_f32_e32 v55, v226, v255
	v_and_b32_e32 v255, 0xffff0000, v249
	v_fmac_f32_e32 v51, v226, v255
	v_cvt_pk_bf16_f32 v248, v71, v63
	v_cvt_pk_bf16_f32 v249, v55, v51
	ds_write_b64 v56, v[248:249] offset:24
	ds_read_b64 v[248:249], v57 offset:520
	s_waitcnt lgkmcnt(2)
	v_lshlrev_b32_e32 v255, 16, v58
	v_fmac_f32_e32 v44, v226, v255
	v_and_b32_e32 v255, 0xffff0000, v58
	v_fmac_f32_e32 v40, v226, v255
	v_lshlrev_b32_e32 v255, 16, v59
	v_fmac_f32_e32 v36, v226, v255
	v_and_b32_e32 v255, 0xffff0000, v59
	v_fmac_f32_e32 v32, v226, v255
	v_cvt_pk_bf16_f32 v58, v44, v40
	v_cvt_pk_bf16_f32 v59, v36, v32
	ds_write_b64 v56, v[58:59] offset:512
	ds_read_b64 v[58:59], v57 offset:528
	s_waitcnt lgkmcnt(2)
	v_lshlrev_b32_e32 v255, 16, v248
	v_fmac_f32_e32 v45, v226, v255
	v_and_b32_e32 v255, 0xffff0000, v248
	v_fmac_f32_e32 v41, v226, v255
	v_lshlrev_b32_e32 v255, 16, v249
	v_fmac_f32_e32 v37, v226, v255
	v_and_b32_e32 v255, 0xffff0000, v249
	v_fmac_f32_e32 v33, v226, v255
	v_cvt_pk_bf16_f32 v248, v45, v41
	v_cvt_pk_bf16_f32 v249, v37, v33
	ds_write_b64 v56, v[248:249] offset:520
	ds_read_b64 v[248:249], v57 offset:536
	s_waitcnt lgkmcnt(2)
	v_lshlrev_b32_e32 v255, 16, v58
	v_fmac_f32_e32 v46, v226, v255
	v_and_b32_e32 v255, 0xffff0000, v58
	v_fmac_f32_e32 v42, v226, v255
	v_lshlrev_b32_e32 v255, 16, v59
	v_fmac_f32_e32 v38, v226, v255
	v_and_b32_e32 v255, 0xffff0000, v59
	v_fmac_f32_e32 v34, v226, v255
	v_cvt_pk_bf16_f32 v58, v46, v42
	v_cvt_pk_bf16_f32 v59, v38, v34
	ds_write_b64 v56, v[58:59] offset:528
	s_waitcnt lgkmcnt(1)
	v_lshlrev_b32_e32 v255, 16, v248
	v_fmac_f32_e32 v47, v226, v255
	v_and_b32_e32 v255, 0xffff0000, v248
	v_fmac_f32_e32 v43, v226, v255
	v_lshlrev_b32_e32 v255, 16, v249
	v_fmac_f32_e32 v39, v226, v255
	v_and_b32_e32 v255, 0xffff0000, v249
	v_fmac_f32_e32 v35, v226, v255
	v_cvt_pk_bf16_f32 v248, v47, v43
	v_cvt_pk_bf16_f32 v249, v39, v35
	ds_write_b64 v56, v[248:249] offset:536
	s_waitcnt lgkmcnt(0)
	s_barrier
	s_and_saveexec_b64 s[6:7], s[42:43]
	s_cbranch_execnz .LBB0_557
	s_or_b64 exec, exec, s[6:7]
	s_and_saveexec_b64 s[6:7], s[44:45]
	s_cbranch_execnz .LBB0_558

; __global__ void __launch_bounds__(NTHR, 2) mega_fwd(Params p) {
	.amdhsa_kernel _Z8mega_fwd6Params
		.amdhsa_group_segment_fixed_size 0
		.amdhsa_private_segment_fixed_size 0
		.amdhsa_kernarg_size 528
		.amdhsa_user_sgpr_count 2
		.amdhsa_user_sgpr_dispatch_ptr 0
		.amdhsa_user_sgpr_queue_ptr 0
		.amdhsa_user_sgpr_kernarg_segment_ptr 1
		.amdhsa_user_sgpr_dispatch_id 0
		.amdhsa_user_sgpr_kernarg_preload_length 0
		.amdhsa_user_sgpr_kernarg_preload_offset 0
		.amdhsa_user_sgpr_private_segment_size 0
		.amdhsa_uses_dynamic_stack 0
		.amdhsa_enable_private_segment 0
		.amdhsa_system_sgpr_workgroup_id_x 1
		.amdhsa_system_sgpr_workgroup_id_y 0
		.amdhsa_system_sgpr_workgroup_id_z 0
		.amdhsa_system_sgpr_workgroup_info 0
		.amdhsa_system_vgpr_workitem_id 2
		.amdhsa_next_free_vgpr 256
		.amdhsa_next_free_sgpr 100
		.amdhsa_accum_offset 256
		.amdhsa_reserve_vcc 1
		.amdhsa_float_round_mode_32 0
		.amdhsa_float_round_mode_16_64 0
		.amdhsa_float_denorm_mode_32 3
		.amdhsa_float_denorm_mode_16_64 3
		.amdhsa_dx10_clamp 1
		.amdhsa_ieee_mode 1
		.amdhsa_fp16_overflow 0
		.amdhsa_tg_split 0
		.amdhsa_exception_fp_ieee_invalid_op 0
		.amdhsa_exception_fp_denorm_src 0
		.amdhsa_exception_fp_ieee_div_zero 0
		.amdhsa_exception_fp_ieee_overflow 0
		.amdhsa_exception_fp_ieee_underflow 0
		.amdhsa_exception_fp_ieee_inexact 0
		.amdhsa_exception_int_div_zero 0
	.end_amdhsa_kernel

; __global__ void __launch_bounds__(NTHR, 2) mega_fwd(Params p) {
amdhsa.kernels:
  - .agpr_count:     0
    .args:
      - .offset:         0
        .size:           272
        .value_kind:     by_value
      - .offset:         272
        .size:           4
        .value_kind:     hidden_block_count_x
      - .offset:         276
        .size:           4
        .value_kind:     hidden_block_count_y
      - .offset:         280
        .size:           4
        .value_kind:     hidden_block_count_z
      - .offset:         284
        .size:           2
        .value_kind:     hidden_group_size_x
      - .offset:         286
        .size:           2
        .value_kind:     hidden_group_size_y
      - .offset:         288
        .size:           2
        .value_kind:     hidden_group_size_z
      - .offset:         290
        .size:           2
        .value_kind:     hidden_remainder_x
      - .offset:         292
        .size:           2
        .value_kind:     hidden_remainder_y
      - .offset:         294
        .size:           2
        .value_kind:     hidden_remainder_z
      - .offset:         312
        .size:           8
        .value_kind:     hidden_global_offset_x
      - .offset:         320
        .size:           8
        .value_kind:     hidden_global_offset_y
      - .offset:         328
        .size:           8
        .value_kind:     hidden_global_offset_z
      - .offset:         336
        .size:           2
        .value_kind:     hidden_grid_dims
      - .offset:         360
        .size:           8
        .value_kind:     hidden_multigrid_sync_arg
      - .offset:         392
        .size:           4
        .value_kind:     hidden_dynamic_lds_size
    .group_segment_fixed_size: 0
    .kernarg_segment_align: 8
    .kernarg_segment_size: 528
    .language:       OpenCL C
    .language_version:
      - 2
      - 0
    .max_flat_workgroup_size: 512
    .name:           _Z8mega_fwd6Params
    .private_segment_fixed_size: 0
    .sgpr_count:     106
    .sgpr_spill_count: 291
    .symbol:         _Z8mega_fwd6Params.kd
    .uniform_work_group_size: 1
    .uses_dynamic_stack: false
    .vgpr_count:     256
    .vgpr_spill_count: 0
    .wavefront_size: 64
